# sample-item loop: 8x8 triangular solve preloads all 28 multipliers (one LDS wait instead of 7 serialized round trips); on top of v8
# speedup vs baseline: 1.0238x; 1.0002x over previous
.LBB0_1069:
	s_or_b64 exec, exec, s[2:3]
	s_waitcnt lgkmcnt(0)
	s_barrier
	v_lshl_add_u32 v98, v100, 2, 0
	s_and_saveexec_b64 s[0:1], vcc
	s_cbranch_execz .LBB0_1071
	ds_read_b32 v204, v105 offset:47968
	ds_read_b64 v[206:207], v105 offset:48000
	ds_read_b96 v[208:210], v105 offset:48032
	ds_read_b128 v[212:215], v105 offset:48064
	ds_read_b128 v[216:219], v105 offset:48096
	ds_read_b32 v205, v105 offset:48112
	ds_read_b128 v[220:223], v105 offset:48128
	ds_read_b64 v[224:225], v105 offset:48144
	ds_read_b128 v[226:229], v105 offset:48160
	ds_read_b96 v[230:232], v105 offset:48176
	v_cmp_eq_u32_e32 vcc, 0, v100
	s_nop 1
	v_cndmask_b32_e64 v99, 0, 1.0, vcc
	ds_write_b32 v98, v99 offset:48448
	s_waitcnt lgkmcnt(0)
	v_cmp_eq_u32_e32 vcc, 1, v100
	s_nop 1
	v_cndmask_b32_e64 v233, 0, 1.0, vcc
	v_fma_f32 v101, -v99, v204, v233
	ds_write_b32 v98, v101 offset:48480
	v_cmp_eq_u32_e32 vcc, 2, v100
	s_nop 1
	v_cndmask_b32_e64 v233, 0, 1.0, vcc
	v_fma_f32 v233, -v99, v206, v233
	v_fma_f32 v111, -v101, v207, v233
	ds_write_b32 v98, v111 offset:48512
	v_cmp_eq_u32_e32 vcc, 3, v100
	s_nop 1
	v_cndmask_b32_e64 v233, 0, 1.0, vcc
	v_fma_f32 v233, -v99, v208, v233
	v_fma_f32 v233, -v101, v209, v233
	v_fma_f32 v113, -v111, v210, v233
	ds_write_b32 v98, v113 offset:48544
	v_cmp_eq_u32_e32 vcc, 4, v100
	s_nop 1
	v_cndmask_b32_e64 v233, 0, 1.0, vcc
	v_fma_f32 v233, -v99, v212, v233
	v_fma_f32 v233, -v101, v213, v233
	v_fma_f32 v233, -v111, v214, v233
	v_fma_f32 v115, -v113, v215, v233
	ds_write_b32 v98, v115 offset:48576
	v_cmp_eq_u32_e32 vcc, 5, v100
	s_nop 1
	v_cndmask_b32_e64 v233, 0, 1.0, vcc
	v_fma_f32 v233, -v99, v216, v233
	v_fma_f32 v233, -v101, v217, v233
	v_fma_f32 v233, -v111, v218, v233
	v_fma_f32 v233, -v113, v219, v233
	v_fma_f32 v117, -v115, v205, v233
	ds_write_b32 v98, v117 offset:48608
	v_cmp_eq_u32_e32 vcc, 6, v100
	s_nop 1
	v_cndmask_b32_e64 v233, 0, 1.0, vcc
	v_fma_f32 v233, -v99, v220, v233
	v_fma_f32 v233, -v101, v221, v233
	v_fma_f32 v233, -v111, v222, v233
	v_fma_f32 v233, -v113, v223, v233
	v_fma_f32 v233, -v115, v224, v233
	v_fma_f32 v121, -v117, v225, v233
	ds_write_b32 v98, v121 offset:48640
	v_cmp_eq_u32_e32 vcc, 7, v100
	s_nop 1
	v_cndmask_b32_e64 v233, 0, 1.0, vcc
	v_fma_f32 v233, -v99, v226, v233
	v_fma_f32 v233, -v101, v227, v233
	v_fma_f32 v233, -v111, v228, v233
	v_fma_f32 v233, -v113, v229, v233
	v_fma_f32 v233, -v115, v230, v233
	v_fma_f32 v233, -v117, v231, v233
	v_fma_f32 v99, -v121, v232, v233
	ds_write_b32 v98, v99 offset:48672
